# scoring prologue: dead address arithmetic (left over from the replaced head-weight and prefetched loads) removed, 131 instructions
# speedup vs baseline: 1.0124x; 1.0013x over previous
.LBB0_412:
	s_or_b64 exec, exec, s[0:1]
	s_lshl_b32 s0, s36, 2
	s_sub_i32 s38, 0x200c, s0
	s_sub_i32 s80, 0x210c, s0
	s_cmpk_gt_u32 s80, 0xff
	s_cselect_b64 s[0:1], -1, 0
	s_lshr_b32 s81, s80, 8
	v_mov_b32_e32 v172, v184
	s_cmpk_lt_u32 s80, 0x100
	s_cbranch_scc1 .LBB0_439
	v_readlane_b32 s36, v250, 46
	s_ashr_i32 s39, s38, 31
	v_ashrrev_i32_e32 v0, 5, v172
	v_lshlrev_b32_e32 v168, 3, v172
	v_readlane_b32 s37, v250, 47
	s_lshl_b64 s[48:49], s[38:39], 14
	s_nop 0
	v_lshl_add_u64 v[96:97], v[168:169], 1, s[36:37]
	s_movk_i32 s15, 0x1000
	v_readlane_b32 s58, v250, 57
	v_lshlrev_b32_e32 v4, 5, v172
	s_add_i32 s39, s81, 0x7ffffff
	v_and_b32_e32 v168, 0x380, v4
	s_lshl_b32 s44, s39, 5
	s_cmpk_lt_u32 s80, 0x300
	s_cselect_b32 s36, s44, 64
	s_add_i32 s36, s36, s76
	s_or_b32 s42, s36, 3
	s_ashr_i32 s43, s42, 31
	s_lshl_b64 s[42:43], s[42:43], 10
	v_lshl_add_u64 v[2:3], v[96:97], 0, s[42:43]
	s_or_b32 s42, s36, 2
	s_ashr_i32 s43, s42, 31
	s_lshl_b64 s[42:43], s[42:43], 10
	v_lshl_add_u64 v[4:5], v[96:97], 0, s[42:43]
	s_or_b32 s42, s36, 1
	s_ashr_i32 s43, s42, 31
	s_ashr_i32 s37, s36, 31
	s_lshl_b64 s[42:43], s[42:43], 10
	s_lshl_b64 s[36:37], s[36:37], 10
	global_load_dwordx4 v[48:51], v[2:3], off
	global_load_dwordx4 v[52:55], v[4:5], off
	v_lshl_add_u64 v[4:5], v[96:97], 0, s[36:37]
	v_lshl_add_u64 v[2:3], v[96:97], 0, s[42:43]
	global_load_dwordx4 v[56:59], v[2:3], off
	global_load_dwordx4 v[60:63], v[4:5], off
	v_lshrrev_b32_e32 v240, 5, v172
	v_sub_u32_e32 v240, 1, v240
	v_lshlrev_b32_e32 v240, 4, v240
	s_waitcnt vmcnt(4)
	v_lshlrev_b32_e32 v242, v240, v224
	v_and_b32_e32 v98, 0xffff0000, v242
	v_lshlrev_b32_e32 v242, v240, v228
	v_and_b32_e32 v106, 0xffff0000, v242
	v_lshlrev_b32_e32 v242, v240, v232
	v_and_b32_e32 v100, 0xffff0000, v242
	v_lshlrev_b32_e32 v242, v240, v236
	v_and_b32_e32 v107, 0xffff0000, v242
	v_lshlrev_b32_e32 v242, v240, v225
	v_and_b32_e32 v99, 0xffff0000, v242
	v_lshlrev_b32_e32 v242, v240, v229
	v_and_b32_e32 v108, 0xffff0000, v242
	v_lshlrev_b32_e32 v242, v240, v233
	v_and_b32_e32 v101, 0xffff0000, v242
	v_lshlrev_b32_e32 v242, v240, v237
	v_and_b32_e32 v109, 0xffff0000, v242
	v_lshlrev_b32_e32 v242, v240, v226
	v_and_b32_e32 v102, 0xffff0000, v242
	v_lshlrev_b32_e32 v242, v240, v230
	v_and_b32_e32 v110, 0xffff0000, v242
	v_lshlrev_b32_e32 v242, v240, v234
	v_and_b32_e32 v104, 0xffff0000, v242
	v_lshlrev_b32_e32 v242, v240, v238
	v_and_b32_e32 v111, 0xffff0000, v242
	v_lshlrev_b32_e32 v242, v240, v227
	v_and_b32_e32 v103, 0xffff0000, v242
	v_lshlrev_b32_e32 v242, v240, v231
	v_and_b32_e32 v112, 0xffff0000, v242
	v_lshlrev_b32_e32 v242, v240, v235
	v_and_b32_e32 v105, 0xffff0000, v242
	v_lshlrev_b32_e32 v242, v240, v239
	v_and_b32_e32 v113, 0xffff0000, v242
	v_lshlrev_b32_e32 v1, 1, v0
	s_mov_b32 s36, 0x10800
	v_and_b32_e32 v2, 31, v172
	v_mul_lo_u32 v3, v0, s36
	v_lshl_add_u32 v115, v0, 13, s17
	v_or_b32_e32 v0, 1, v1
	v_add_u32_e32 v116, s38, v0
	v_lshl_add_u32 v117, v0, 12, s17
	v_lshl_or_b32 v0, v2, 2, v3
	v_add_u32_e32 v114, s38, v1
	v_add_u32_e32 v118, s4, v2
	v_add_u32_e32 v119, s14, v0
	s_waitcnt vmcnt(4)
	v_mov_b32_e32 v36, v80
	v_mov_b32_e32 v37, v81
	v_mov_b32_e32 v38, v82
	v_mov_b32_e32 v39, v83
	v_mov_b32_e32 v32, v84
	v_mov_b32_e32 v33, v85
	v_mov_b32_e32 v34, v86
	v_mov_b32_e32 v35, v87
	v_mov_b32_e32 v44, v88
	v_mov_b32_e32 v45, v89
	v_mov_b32_e32 v46, v90
	v_mov_b32_e32 v47, v91
	v_mov_b32_e32 v40, v92
	v_mov_b32_e32 v41, v93
	v_mov_b32_e32 v42, v94
	v_mov_b32_e32 v43, v95
	v_mov_b32_e32 v76, v206
	v_mov_b32_e32 v77, v207
	v_mov_b32_e32 v78, v208
	v_mov_b32_e32 v79, v209
	v_mov_b32_e32 v72, v210
	v_mov_b32_e32 v73, v211
	v_mov_b32_e32 v74, v212
	v_mov_b32_e32 v75, v213
	v_mov_b32_e32 v68, v214
	v_mov_b32_e32 v69, v215
	v_mov_b32_e32 v70, v216
	v_mov_b32_e32 v71, v217
	v_mov_b32_e32 v64, v218
	v_mov_b32_e32 v65, v219
	v_mov_b32_e32 v66, v220
	v_mov_b32_e32 v67, v221
	v_mov_b32_e32 v28, v198
	v_mov_b32_e32 v29, v199
	v_mov_b32_e32 v30, v200
	v_mov_b32_e32 v31, v201
	v_mov_b32_e32 v20, v244
	v_mov_b32_e32 v21, v245
	v_mov_b32_e32 v22, v246
	v_mov_b32_e32 v23, v247
	v_mov_b32_e32 v16, v160
	v_mov_b32_e32 v17, v161
	v_mov_b32_e32 v18, v162
	v_mov_b32_e32 v19, v163
	v_mov_b32_e32 v24, v176
	v_mov_b32_e32 v25, v177
	v_mov_b32_e32 v26, v178
	v_mov_b32_e32 v27, v179
	s_mov_b32 s46, 6
	s_branch .LBB0_416
